# all hipcc s_setprio flips removed; one static s_setprio 1 for waves 4-7 at each GEMM instance start, reset to 0 at non-GEMM phase entries
# baseline (speedup 1.0000x reference)
.LBB0_175:
	s_andn2_b64 vcc, exec, s[0:1]
	s_cbranch_vccnz .LBB0_227
	v_ashrrev_i32_e32 v1, 31, v8
	v_lshrrev_b32_e32 v1, 26, v1
	v_add_u32_e32 v1, v8, v1
	v_ashrrev_i32_e32 v9, 6, v1
	v_bfe_i32 v1, v8, 27, 1
	v_lshlrev_b32_e32 v0, 4, v8
	v_lshrrev_b32_e32 v1, 22, v1
	v_add_u32_e32 v1, v0, v1
	v_and_b32_e32 v1, 0xfffffc00, v1
	v_sub_u32_e32 v1, v0, v1
	v_lshrrev_b32_e32 v2, 4, v1
	v_bitop3_b32 v1, v2, v1, 32 bitop3:0x6c
	v_ashrrev_i32_e32 v3, 31, v1
	v_lshrrev_b32_e32 v3, 26, v3
	v_add_u32_e32 v3, v1, v3
	v_lshlrev_b32_e32 v2, 3, v9
	v_ashrrev_i32_e32 v10, 6, v3
	v_and_b32_e32 v3, 0xc0, v3
	v_and_b32_e32 v2, -16, v2
	v_sub_u32_e32 v1, v1, v3
	v_mov_b32_e32 v6, 1
	v_add_u32_e32 v2, v10, v2
	v_ashrrev_i16_sdwa v1, v6, sext(v1) dst_sel:DWORD dst_unused:UNUSED_PAD src0_sel:DWORD src1_sel:BYTE_0
	v_lshlrev_b32_e32 v4, 5, v9
	v_bfe_i32 v11, v1, 0, 16
	v_lshlrev_b32_e32 v1, 1, v2
	v_lshrrev_b32_e32 v3, 2, v2
	v_and_b32_e32 v5, 3, v10
	s_mov_b32 s1, 0x1fffe0
	v_and_b32_e32 v4, 32, v4
	v_and_b32_e32 v1, 24, v1
	v_and_b32_e32 v3, 4, v3
	v_and_or_b32 v5, v2, s1, v5
	v_or3_b32 v1, v5, v3, v1
	v_add_lshl_u32 v3, v4, v11, 1
	v_add_u32_e32 v0, 0x2000, v0
	v_lshl_add_u32 v232, v1, 11, v3
	v_ashrrev_i32_e32 v1, 31, v0
	v_lshrrev_b32_e32 v1, 22, v1
	v_add_u32_e32 v1, v0, v1
	v_ashrrev_i32_e32 v12, 10, v1
	v_mul_i32_i24_e32 v1, 0x400, v12
	v_sub_u32_e32 v0, v0, v1
	v_lshrrev_b32_e32 v1, 4, v0
	v_bitop3_b32 v0, v1, v0, 32 bitop3:0x6c
	v_lshl_add_u32 v128, v2, 11, v3
	v_ashrrev_i32_e32 v2, 31, v0
	s_add_u32 s30, s8, 0x3a00000
	v_lshrrev_b32_e32 v2, 26, v2
	s_addc_u32 s31, s9, 0
	v_lshlrev_b32_e32 v1, 3, v12
	v_add_u32_e32 v2, v0, v2
	s_add_u32 s34, s8, 0x200000
	v_and_b32_e32 v1, -16, v1
	v_ashrrev_i32_e32 v13, 6, v2
	s_addc_u32 s35, s9, 0
	s_ashr_i32 s0, s10, 6
	v_add_u32_e32 v1, v13, v1
	v_and_b32_e32 v2, 0xc0, v2
	v_and_b32_e32 v4, 3, v13
	s_ashr_i32 s21, s20, 31
	s_ashr_i32 s3, s2, 31
	v_sub_u32_e32 v0, v0, v2
	v_and_or_b32 v4, v1, s1, v4
	s_ashr_i32 s1, s10, 8
	s_lshl_b32 s36, s0, 10
	s_lshl_b64 s[6:7], s[20:21], 19
	s_lshl_b64 s[12:13], s[2:3], 19
	v_ashrrev_i16_sdwa v0, v6, sext(v0) dst_sel:DWORD dst_unused:UNUSED_PAD src0_sel:DWORD src1_sel:BYTE_0
	s_add_u32 s22, s34, s12
	v_lshlrev_b32_e32 v3, 5, v12
	v_bfe_i32 v14, v0, 0, 16
	v_lshlrev_b32_e32 v0, 1, v1
	v_lshrrev_b32_e32 v2, 2, v1
	s_addc_u32 s23, s35, s13
	s_add_i32 s37, s36, 0
	v_and_b32_e32 v3, 32, v3
	v_and_b32_e32 v0, 24, v0
	v_and_b32_e32 v2, 4, v2
	s_add_i32 m0, s37, 0x10000
	v_or3_b32 v0, v4, v2, v0
	v_add_lshl_u32 v2, v3, v14, 1
	global_load_lds_dwordx4 v232, s[22:23]
	s_add_i32 m0, s37, 0x12000
	v_lshl_add_u32 v132, v0, 11, v2
	s_add_u32 s12, s22, 0x40000
	global_load_lds_dwordx4 v132, s[22:23]
	s_addc_u32 s13, s23, 0
	s_add_i32 m0, s37, 0x14000
	v_lshl_add_u32 v130, v1, 11, v2
	global_load_lds_dwordx4 v232, s[12:13]
	s_add_i32 m0, s37, 0x16000
	s_add_u32 s24, s30, s6
	s_addc_u32 s25, s31, s7
	s_add_i32 s38, s37, 0x2000
	global_load_lds_dwordx4 v132, s[12:13]
	s_mov_b32 m0, s37
	s_add_u32 s6, s24, 0x40000
	global_load_lds_dwordx4 v128, s[24:25]
	s_mov_b32 m0, s38
	s_addc_u32 s7, s25, 0
	s_add_i32 s39, s37, 0x4000
	global_load_lds_dwordx4 v130, s[24:25]
	s_mov_b32 m0, s39
	s_add_i32 s40, s37, 0x6000
	global_load_lds_dwordx4 v128, s[6:7]
	s_mov_b32 m0, s40
	v_mov_b32_e32 v133, v233
	global_load_lds_dwordx4 v130, s[6:7]
	v_mov_b32_e32 v129, v233
	v_mov_b32_e32 v131, v233
	s_cmp_eq_u32 s1, 1
	v_lshl_add_u64 v[6:7], s[22:23], 0, v[232:233]
	v_lshl_add_u64 v[4:5], s[22:23], 0, v[132:133]
	v_lshl_add_u64 v[0:1], s[24:25], 0, v[128:129]
	s_cselect_b64 s[6:7], -1, 0
	s_cmp_lg_u32 s1, 1
	v_lshl_add_u64 v[2:3], s[24:25], 0, v[130:131]
	s_cbranch_scc1 .LBB0_178
	s_setprio 1
	s_barrier

.LBB0_275:
	s_setprio 0
	s_cmp_le_i32 s86, s38
	s_cselect_b64 s[0:1], -1, 0
	s_and_b64 s[2:3], s[0:1], s[34:35]
	s_andn2_b64 vcc, exec, s[2:3]
	s_cbranch_vccnz .LBB0_408
	v_mbcnt_lo_u32_b32 v0, -1, 0
	v_mbcnt_hi_u32_b32 v0, -1, v0
	s_mov_b32 s16, s74
	v_add_u32_e32 v2, s88, v0
	s_mov_b32 s17, s73
	v_mov_b32_e32 v0, s75
	ds_read_b64 v[0:1], v0
	v_readfirstlane_b32 s2, v2
	v_mov_b32_e32 v3, v233
	s_mov_b64 s[12:13], 0x2900000
	s_mov_b32 s20, 0
	s_waitcnt lgkmcnt(0)
	v_readfirstlane_b32 s6, v0
	v_readfirstlane_b32 s7, v1
	s_add_u32 s8, s6, 0x7a00000
	s_addc_u32 s9, s7, 0
	s_add_u32 s10, s6, 0x10000
	v_and_b32_e32 v1, 7, v2
	s_addc_u32 s11, s7, 0
	s_ashr_i32 s2, s2, 1
	v_lshrrev_b32_e32 v0, 3, v2
	v_lshlrev_b32_e32 v2, 4, v1
	s_andn2_b32 s2, s2, 31
	v_lshl_add_u64 v[6:7], s[6:7], 0, v[2:3]
	v_lshlrev_b32_e32 v232, 3, v1
	v_and_or_b32 v18, v0, 7, s2
	v_lshlrev_b32_e32 v0, 5, v1
	v_lshlrev_b32_e32 v12, 2, v1
	v_lshl_add_u64 v[4:5], v[6:7], 0, s[12:13]
	s_mov_b64 s[12:13], 0x2980000
	v_lshl_add_u64 v[8:9], s[6:7], 0, v[232:233]
	s_mov_b64 s[6:7], 0x1f200000
	s_ashr_i32 s18, s16, 31
	s_ashr_i32 s19, s17, 31
	v_cmp_eq_u32_e64 s[2:3], 0, v1
	v_cmp_gt_u32_e64 s[4:5], 4, v1
	v_lshl_add_u64 v[6:7], v[6:7], 0, s[12:13]
	v_lshl_add_u64 v[8:9], v[8:9], 0, s[6:7]
	v_lshlrev_b32_e32 v232, 1, v0
	v_lshlrev_b32_e32 v10, 1, v2
	v_lshlrev_b32_e32 v12, 1, v12
	s_branch .LBB0_279

.LBB0_298:
	s_andn2_b64 vcc, exec, s[2:3]
	s_cbranch_vccnz .LBB0_350
	v_bfe_i32 v2, v8, 27, 1
	v_lshlrev_b32_e32 v0, 4, v8
	v_lshrrev_b32_e32 v2, 22, v2
	v_add_u32_e32 v2, v0, v2
	v_and_b32_e32 v2, 0xfffffc00, v2
	v_sub_u32_e32 v2, v0, v2
	v_ashrrev_i32_e32 v1, 31, v8
	v_lshrrev_b32_e32 v3, 4, v2
	v_lshrrev_b32_e32 v1, 26, v1
	v_bitop3_b32 v2, v3, v2, 32 bitop3:0x6c
	v_add_u32_e32 v1, v8, v1
	v_ashrrev_i32_e32 v4, 31, v2
	v_ashrrev_i32_e32 v1, 6, v1
	v_lshrrev_b32_e32 v4, 26, v4
	v_lshlrev_b32_e32 v3, 3, v1
	v_add_u32_e32 v4, v2, v4
	v_and_b32_e32 v3, -16, v3
	v_ashrrev_i32_e32 v5, 6, v4
	v_and_b32_e32 v4, 0xc0, v4
	v_add_u32_e32 v3, v5, v3
	v_sub_u32_e32 v2, v2, v4
	v_mov_b32_e32 v7, 1
	v_lshlrev_b32_e32 v1, 5, v1
	v_ashrrev_i16_sdwa v2, v7, sext(v2) dst_sel:DWORD dst_unused:UNUSED_PAD src0_sel:DWORD src1_sel:BYTE_0
	v_lshlrev_b32_e32 v4, 1, v3
	v_lshrrev_b32_e32 v6, 2, v3
	v_and_b32_e32 v5, 3, v5
	s_mov_b32 s3, 0x7fffe0
	v_and_b32_e32 v1, 32, v1
	v_bfe_i32 v2, v2, 0, 16
	v_and_b32_e32 v4, 24, v4
	v_and_b32_e32 v6, 4, v6
	v_and_or_b32 v5, v3, s3, v5
	v_or3_b32 v4, v5, v6, v4
	v_add_lshl_u32 v1, v1, v2, 1
	v_add_u32_e32 v0, 0x2000, v0
	v_lshl_add_u32 v128, v3, 13, v1
	v_lshl_add_u32 v232, v4, 9, v1
	v_ashrrev_i32_e32 v1, 31, v0
	v_lshrrev_b32_e32 v1, 22, v1
	v_add_u32_e32 v1, v0, v1
	v_ashrrev_i32_e32 v1, 10, v1
	v_mul_i32_i24_e32 v2, 0x400, v1
	v_sub_u32_e32 v0, v0, v2
	v_lshrrev_b32_e32 v2, 4, v0
	v_bitop3_b32 v0, v2, v0, 32 bitop3:0x6c
	v_ashrrev_i32_e32 v3, 31, v0
	s_add_u32 s46, s10, 0x7a00000
	v_lshrrev_b32_e32 v3, 26, v3
	s_addc_u32 s47, s11, 0
	v_lshlrev_b32_e32 v2, 3, v1
	v_add_u32_e32 v3, v0, v3
	s_add_u32 s48, s10, 0x2880000
	v_and_b32_e32 v2, -16, v2
	v_ashrrev_i32_e32 v4, 6, v3
	s_addc_u32 s49, s11, 0
	s_ashr_i32 s2, s12, 6
	v_add_u32_e32 v2, v4, v2
	v_and_b32_e32 v4, 3, v4
	s_ashr_i32 s23, s22, 31
	s_ashr_i32 s5, s4, 31
	v_and_b32_e32 v3, 0xc0, v3
	v_and_or_b32 v4, v2, s3, v4
	s_ashr_i32 s3, s12, 8
	s_lshl_b32 s50, s2, 10
	s_lshl_b64 s[6:7], s[22:23], 21
	s_lshl_b64 s[8:9], s[4:5], 17
	v_sub_u32_e32 v0, v0, v3
	s_add_u32 s24, s48, s8
	v_lshlrev_b32_e32 v1, 5, v1
	v_ashrrev_i16_sdwa v0, v7, sext(v0) dst_sel:DWORD dst_unused:UNUSED_PAD src0_sel:DWORD src1_sel:BYTE_0
	v_lshlrev_b32_e32 v3, 1, v2
	v_lshrrev_b32_e32 v5, 2, v2
	s_addc_u32 s25, s49, s9
	s_add_i32 s51, s50, 0
	v_and_b32_e32 v1, 32, v1
	v_bfe_i32 v0, v0, 0, 16
	v_and_b32_e32 v3, 24, v3
	v_and_b32_e32 v5, 4, v5
	s_add_i32 m0, s51, 0x10000
	v_or3_b32 v3, v4, v5, v3
	v_add_lshl_u32 v0, v1, v0, 1
	global_load_lds_dwordx4 v232, s[24:25]
	s_add_i32 m0, s51, 0x12000
	v_lshl_add_u32 v132, v3, 9, v0
	s_add_u32 s8, s24, 0x10000
	global_load_lds_dwordx4 v132, s[24:25]
	s_addc_u32 s9, s25, 0
	s_add_i32 m0, s51, 0x14000
	v_lshl_add_u32 v130, v2, 13, v0
	global_load_lds_dwordx4 v232, s[8:9]
	s_add_i32 m0, s51, 0x16000
	s_add_u32 s26, s46, s6
	s_addc_u32 s27, s47, s7
	s_add_i32 s52, s51, 0x2000
	global_load_lds_dwordx4 v132, s[8:9]
	s_mov_b32 m0, s51
	s_add_u32 s6, s26, 0x100000
	global_load_lds_dwordx4 v128, s[26:27]
	s_mov_b32 m0, s52
	s_addc_u32 s7, s27, 0
	s_add_i32 s53, s51, 0x4000
	global_load_lds_dwordx4 v130, s[26:27]
	s_mov_b32 m0, s53
	s_add_i32 s54, s51, 0x6000
	global_load_lds_dwordx4 v128, s[6:7]
	s_mov_b32 m0, s54
	v_mov_b32_e32 v133, v233
	global_load_lds_dwordx4 v130, s[6:7]
	v_mov_b32_e32 v129, v233
	v_mov_b32_e32 v131, v233
	s_cmp_eq_u32 s3, 1
	v_lshl_add_u64 v[6:7], s[24:25], 0, v[232:233]
	v_lshl_add_u64 v[4:5], s[24:25], 0, v[132:133]
	v_lshl_add_u64 v[0:1], s[26:27], 0, v[128:129]
	s_cselect_b64 s[6:7], -1, 0
	s_cmp_lg_u32 s3, 1
	v_lshl_add_u64 v[2:3], s[26:27], 0, v[130:131]
	s_cbranch_scc1 .LBB0_301
	s_setprio 1
	s_barrier

.LBB0_356:
	s_andn2_b64 vcc, exec, s[2:3]
	s_cbranch_vccnz .LBB0_408
	v_bfe_i32 v2, v8, 27, 1
	v_lshlrev_b32_e32 v0, 4, v8
	v_lshrrev_b32_e32 v2, 22, v2
	v_add_u32_e32 v2, v0, v2
	v_and_b32_e32 v2, 0xfffffc00, v2
	v_sub_u32_e32 v2, v0, v2
	v_ashrrev_i32_e32 v1, 31, v8
	v_lshrrev_b32_e32 v3, 4, v2
	v_lshrrev_b32_e32 v1, 26, v1
	v_bitop3_b32 v2, v3, v2, 32 bitop3:0x6c
	v_add_u32_e32 v1, v8, v1
	v_ashrrev_i32_e32 v4, 31, v2
	v_ashrrev_i32_e32 v1, 6, v1
	v_lshrrev_b32_e32 v4, 26, v4
	v_lshlrev_b32_e32 v3, 3, v1
	v_add_u32_e32 v4, v2, v4
	v_and_b32_e32 v3, -16, v3
	v_ashrrev_i32_e32 v5, 6, v4
	v_and_b32_e32 v4, 0xc0, v4
	v_add_u32_e32 v3, v5, v3
	v_sub_u32_e32 v2, v2, v4
	v_mov_b32_e32 v7, 1
	v_lshlrev_b32_e32 v1, 5, v1
	v_ashrrev_i16_sdwa v2, v7, sext(v2) dst_sel:DWORD dst_unused:UNUSED_PAD src0_sel:DWORD src1_sel:BYTE_0
	v_lshlrev_b32_e32 v4, 1, v3
	v_lshrrev_b32_e32 v6, 2, v3
	v_and_b32_e32 v5, 3, v5
	s_mov_b32 s3, 0x7fffe0
	v_and_b32_e32 v1, 32, v1
	v_bfe_i32 v2, v2, 0, 16
	v_and_b32_e32 v4, 24, v4
	v_and_b32_e32 v6, 4, v6
	v_and_or_b32 v5, v3, s3, v5
	v_or3_b32 v4, v5, v6, v4
	v_add_lshl_u32 v1, v1, v2, 1
	v_add_u32_e32 v0, 0x2000, v0
	v_lshl_add_u32 v128, v3, 13, v1
	v_lshl_add_u32 v232, v4, 9, v1
	v_ashrrev_i32_e32 v1, 31, v0
	v_lshrrev_b32_e32 v1, 22, v1
	v_add_u32_e32 v1, v0, v1
	v_ashrrev_i32_e32 v1, 10, v1
	v_mul_i32_i24_e32 v2, 0x400, v1
	v_sub_u32_e32 v0, v0, v2
	v_lshrrev_b32_e32 v2, 4, v0
	v_bitop3_b32 v0, v2, v0, 32 bitop3:0x6c
	v_ashrrev_i32_e32 v3, 31, v0
	s_add_u32 s46, s10, 0x7a00200
	v_lshrrev_b32_e32 v3, 26, v3
	s_addc_u32 s47, s11, 0
	v_lshlrev_b32_e32 v2, 3, v1
	v_add_u32_e32 v3, v0, v3
	s_add_u32 s48, s10, 0x28c0000
	v_and_b32_e32 v2, -16, v2
	v_ashrrev_i32_e32 v4, 6, v3
	s_addc_u32 s49, s11, 0
	s_ashr_i32 s2, s12, 6
	v_add_u32_e32 v2, v4, v2
	v_and_b32_e32 v4, 3, v4
	s_ashr_i32 s23, s22, 31
	s_ashr_i32 s5, s4, 31
	v_and_b32_e32 v3, 0xc0, v3
	v_and_or_b32 v4, v2, s3, v4
	s_ashr_i32 s3, s12, 8
	s_lshl_b32 s50, s2, 10
	s_lshl_b64 s[6:7], s[22:23], 21
	s_lshl_b64 s[8:9], s[4:5], 17
	v_sub_u32_e32 v0, v0, v3
	s_add_u32 s24, s48, s8
	v_lshlrev_b32_e32 v1, 5, v1
	v_ashrrev_i16_sdwa v0, v7, sext(v0) dst_sel:DWORD dst_unused:UNUSED_PAD src0_sel:DWORD src1_sel:BYTE_0
	v_lshlrev_b32_e32 v3, 1, v2
	v_lshrrev_b32_e32 v5, 2, v2
	s_addc_u32 s25, s49, s9
	s_add_i32 s51, s50, 0
	v_and_b32_e32 v1, 32, v1
	v_bfe_i32 v0, v0, 0, 16
	v_and_b32_e32 v3, 24, v3
	v_and_b32_e32 v5, 4, v5
	s_add_i32 m0, s51, 0x10000
	v_or3_b32 v3, v4, v5, v3
	v_add_lshl_u32 v0, v1, v0, 1
	global_load_lds_dwordx4 v232, s[24:25]
	s_add_i32 m0, s51, 0x12000
	v_lshl_add_u32 v132, v3, 9, v0
	s_add_u32 s8, s24, 0x10000
	global_load_lds_dwordx4 v132, s[24:25]
	s_addc_u32 s9, s25, 0
	s_add_i32 m0, s51, 0x14000
	v_lshl_add_u32 v130, v2, 13, v0
	global_load_lds_dwordx4 v232, s[8:9]
	s_add_i32 m0, s51, 0x16000
	s_add_u32 s26, s46, s6
	s_addc_u32 s27, s47, s7
	s_add_i32 s52, s51, 0x2000
	global_load_lds_dwordx4 v132, s[8:9]
	s_mov_b32 m0, s51
	s_add_u32 s6, s26, 0x100000
	global_load_lds_dwordx4 v128, s[26:27]
	s_mov_b32 m0, s52
	s_addc_u32 s7, s27, 0
	s_add_i32 s53, s51, 0x4000
	global_load_lds_dwordx4 v130, s[26:27]
	s_mov_b32 m0, s53
	s_add_i32 s54, s51, 0x6000
	global_load_lds_dwordx4 v128, s[6:7]
	s_mov_b32 m0, s54
	v_mov_b32_e32 v133, v233
	global_load_lds_dwordx4 v130, s[6:7]
	v_mov_b32_e32 v129, v233
	v_mov_b32_e32 v131, v233
	s_cmp_eq_u32 s3, 1
	v_lshl_add_u64 v[6:7], s[24:25], 0, v[232:233]
	v_lshl_add_u64 v[4:5], s[24:25], 0, v[132:133]
	v_lshl_add_u64 v[0:1], s[26:27], 0, v[128:129]
	s_cselect_b64 s[6:7], -1, 0
	s_cmp_lg_u32 s3, 1
	v_lshl_add_u64 v[2:3], s[26:27], 0, v[130:131]
	s_cbranch_scc1 .LBB0_359
	s_setprio 1
	s_barrier

.LBB0_456:
	s_setprio 0
	s_cmp_le_i32 s86, s38
	s_cselect_b64 s[0:1], -1, 0
	v_writelane_b32 v254, s0, 62
	v_writelane_b32 v255, s77, 0
	s_nop 0
	v_writelane_b32 v254, s1, 63
	s_and_b64 s[0:1], s[0:1], s[34:35]
	s_andn2_b64 vcc, exec, s[0:1]
	s_cbranch_vccnz .LBB0_791
	v_readlane_b32 s0, v254, 53
	v_readlane_b32 s2, v254, 49
	v_readlane_b32 s3, v254, 48
	v_mov_b32_e32 v0, s0
	ds_read_b64 v[0:1], v0
	v_readlane_b32 s0, v254, 8
	s_mov_b32 s59, 0x80000
	s_waitcnt lgkmcnt(0)
	v_readfirstlane_b32 s96, v0
	v_mov_b32_e32 v0, s0
	v_readlane_b32 s0, v254, 9
	v_readfirstlane_b32 s91, v1
	ds_read_b64 v[0:1], v0
	v_mov_b32_e32 v2, s0
	ds_read_b64 v[2:3], v2
	s_add_u32 s0, s96, 0x17a00000
	s_addc_u32 s1, s91, 0
	s_and_b32 s4, s3, 7
	s_sub_i32 s2, s2, s4
	s_add_i32 s2, s2, 7
	s_ashr_i32 s3, s3, 3
	v_writelane_b32 v255, s4, 1
	s_ashr_i32 s64, s2, 3
	s_waitcnt lgkmcnt(0)
	v_readfirstlane_b32 s30, v1
	v_readfirstlane_b32 s31, v0
	v_readfirstlane_b32 s34, v3
	v_writelane_b32 v255, s3, 2
	s_cmp_gt_i32 s3, 31
	v_readfirstlane_b32 s35, v2
	s_cbranch_scc1 .LBB0_494
	s_add_u32 s36, s96, 0x1ba00000
	s_addc_u32 s37, s91, 0
	s_add_u32 s38, s96, 0x1d200000
	s_addc_u32 s39, s91, 0
	s_add_u32 s40, s96, 0x1f200000
	s_addc_u32 s41, s91, 0
	s_add_u32 s4, s96, 0x2900000
	v_readlane_b32 s2, v255, 1
	s_addc_u32 s5, s91, 0
	s_lshl_b32 s42, s2, 5
	v_readlane_b32 s43, v255, 2
	s_branch .LBB0_460

.LBB0_839:
	s_setprio 0
	s_cmp_le_i32 s86, s38
	s_cselect_b64 s[2:3], -1, 0
	s_and_b64 s[0:1], s[2:3], s[0:1]
	s_andn2_b64 vcc, exec, s[0:1]
	v_readlane_b32 s73, v254, 48
	s_cbranch_vccnz .LBB0_844
	v_mbcnt_lo_u32_b32 v0, -1, 0
	v_mbcnt_hi_u32_b32 v0, -1, v0
	s_mov_b32 s8, s74
	v_add_u32_e32 v0, s88, v0
	s_mov_b32 s9, s73
	v_mov_b32_e32 v1, s75
	ds_read_b64 v[2:3], v1
	v_lshl_add_u32 v5, s9, 9, v0
	s_mov_b32 s4, 0x100000
	v_cmp_gt_i32_e32 vcc, s4, v5
	s_waitcnt lgkmcnt(0)
	v_readfirstlane_b32 s1, v3
	v_readfirstlane_b32 s0, v2
	s_and_saveexec_b64 s[4:5], vcc
	s_mov_b32 s14, 0xfffff
	s_cbranch_execz .LBB0_843
	s_lshl_b32 s10, s8, 9
	s_add_u32 s6, s0, 0x80000
	v_lshlrev_b32_e32 v0, 3, v0
	s_addc_u32 s7, s1, 0
	v_lshl_add_u32 v6, s9, 12, v0
	s_lshl_b32 s11, s8, 12
	s_mov_b64 s[8:9], 0

.LBB0_899:
	s_andn2_b64 vcc, exec, s[2:3]
	s_cbranch_vccnz .LBB0_951
	v_ashrrev_i32_e32 v1, 31, v11
	v_lshrrev_b32_e32 v1, 26, v1
	v_add_u32_e32 v1, v11, v1
	v_ashrrev_i32_e32 v8, 6, v1
	v_bfe_i32 v1, v11, 27, 1
	v_lshlrev_b32_e32 v0, 4, v11
	v_lshrrev_b32_e32 v1, 22, v1
	v_add_u32_e32 v1, v0, v1
	v_and_b32_e32 v1, 0xfffffc00, v1
	v_sub_u32_e32 v1, v0, v1
	v_lshrrev_b32_e32 v2, 4, v1
	v_bitop3_b32 v1, v2, v1, 32 bitop3:0x6c
	v_ashrrev_i32_e32 v3, 31, v1
	v_lshrrev_b32_e32 v3, 26, v3
	v_add_u32_e32 v3, v1, v3
	v_lshlrev_b32_e32 v2, 3, v8
	v_ashrrev_i32_e32 v9, 6, v3
	v_and_b32_e32 v3, 0xc0, v3
	v_and_b32_e32 v2, -16, v2
	v_sub_u32_e32 v1, v1, v3
	v_mov_b32_e32 v6, 1
	v_add_u32_e32 v2, v9, v2
	v_ashrrev_i16_sdwa v1, v6, sext(v1) dst_sel:DWORD dst_unused:UNUSED_PAD src0_sel:DWORD src1_sel:BYTE_0
	v_lshlrev_b32_e32 v4, 5, v8
	v_bfe_i32 v10, v1, 0, 16
	v_lshlrev_b32_e32 v1, 1, v2
	v_lshrrev_b32_e32 v3, 2, v2
	v_and_b32_e32 v5, 3, v9
	s_mov_b32 s3, 0x1fffe0
	v_and_b32_e32 v4, 32, v4
	v_and_b32_e32 v1, 24, v1
	v_and_b32_e32 v3, 4, v3
	v_and_or_b32 v5, v2, s3, v5
	v_or3_b32 v1, v5, v3, v1
	v_add_lshl_u32 v3, v4, v10, 1
	v_add_u32_e32 v0, 0x2000, v0
	v_lshl_add_u32 v232, v1, 11, v3
	v_ashrrev_i32_e32 v1, 31, v0
	v_lshrrev_b32_e32 v1, 22, v1
	v_add_u32_e32 v1, v0, v1
	v_ashrrev_i32_e32 v12, 10, v1
	v_mul_i32_i24_e32 v1, 0x400, v12
	v_sub_u32_e32 v0, v0, v1
	v_lshrrev_b32_e32 v1, 4, v0
	v_bitop3_b32 v0, v1, v0, 32 bitop3:0x6c
	v_lshl_add_u32 v128, v2, 11, v3
	v_ashrrev_i32_e32 v2, 31, v0
	v_lshrrev_b32_e32 v2, 26, v2
	s_add_u32 s30, s8, 0x3a00000
	v_lshlrev_b32_e32 v1, 3, v12
	v_add_u32_e32 v2, v0, v2
	s_addc_u32 s31, s9, 0
	v_and_b32_e32 v1, -16, v1
	v_ashrrev_i32_e32 v13, 6, v2
	s_add_u32 s34, s8, 0xa00000
	v_add_u32_e32 v1, v13, v1
	v_and_b32_e32 v4, 3, v13
	s_addc_u32 s35, s9, 0
	v_and_b32_e32 v2, 0xc0, v2
	v_and_or_b32 v4, v1, s3, v4
	s_ashr_i32 s3, s10, 6
	s_ashr_i32 s21, s20, 31
	s_ashr_i32 s5, s4, 31
	s_ashr_i32 s2, s10, 8
	v_sub_u32_e32 v0, v0, v2
	s_lshl_b32 s36, s3, 10
	s_lshl_b64 s[6:7], s[20:21], 19
	s_lshl_b64 s[12:13], s[4:5], 19
	v_ashrrev_i16_sdwa v0, v6, sext(v0) dst_sel:DWORD dst_unused:UNUSED_PAD src0_sel:DWORD src1_sel:BYTE_0
	s_add_u32 s22, s34, s12
	v_lshlrev_b32_e32 v3, 5, v12
	v_bfe_i32 v14, v0, 0, 16
	v_lshlrev_b32_e32 v0, 1, v1
	v_lshrrev_b32_e32 v2, 2, v1
	s_addc_u32 s23, s35, s13
	s_add_i32 s37, s36, 0
	v_and_b32_e32 v3, 32, v3
	v_and_b32_e32 v0, 24, v0
	v_and_b32_e32 v2, 4, v2
	s_add_i32 m0, s37, 0x10000
	v_or3_b32 v0, v4, v2, v0
	v_add_lshl_u32 v2, v3, v14, 1
	global_load_lds_dwordx4 v232, s[22:23]
	s_add_i32 m0, s37, 0x12000
	v_lshl_add_u32 v132, v0, 11, v2
	s_add_u32 s12, s22, 0x40000
	global_load_lds_dwordx4 v132, s[22:23]
	s_addc_u32 s13, s23, 0
	s_add_i32 m0, s37, 0x14000
	v_lshl_add_u32 v130, v1, 11, v2
	global_load_lds_dwordx4 v232, s[12:13]
	s_add_i32 m0, s37, 0x16000
	s_add_u32 s24, s30, s6
	s_addc_u32 s25, s31, s7
	s_add_i32 s38, s37, 0x2000
	global_load_lds_dwordx4 v132, s[12:13]
	s_mov_b32 m0, s37
	s_add_u32 s6, s24, 0x40000
	global_load_lds_dwordx4 v128, s[24:25]
	s_mov_b32 m0, s38
	s_addc_u32 s7, s25, 0
	s_add_i32 s39, s37, 0x4000
	global_load_lds_dwordx4 v130, s[24:25]
	s_mov_b32 m0, s39
	s_add_i32 s40, s37, 0x6000
	global_load_lds_dwordx4 v128, s[6:7]
	s_mov_b32 m0, s40
	v_mov_b32_e32 v133, v233
	global_load_lds_dwordx4 v130, s[6:7]
	v_mov_b32_e32 v129, v233
	v_mov_b32_e32 v131, v233
	s_cmp_eq_u32 s2, 1
	v_lshl_add_u64 v[6:7], s[22:23], 0, v[232:233]
	v_lshl_add_u64 v[4:5], s[22:23], 0, v[132:133]
	v_lshl_add_u64 v[0:1], s[24:25], 0, v[128:129]
	s_cselect_b64 s[6:7], -1, 0
	s_cmp_lg_u32 s2, 1
	v_lshl_add_u64 v[2:3], s[24:25], 0, v[130:131]
	s_cbranch_scc1 .LBB0_902
	s_setprio 1
	s_barrier

.LBB0_1006:
	s_andn2_b64 vcc, exec, s[2:3]
	s_cbranch_vccnz .LBB0_1088
	v_bfe_i32 v2, v8, 27, 1
	v_lshlrev_b32_e32 v0, 4, v8
	v_lshrrev_b32_e32 v2, 22, v2
	v_add_u32_e32 v2, v0, v2
	v_and_b32_e32 v2, 0xfffffc00, v2
	v_sub_u32_e32 v2, v0, v2
	v_ashrrev_i32_e32 v1, 31, v8
	v_lshrrev_b32_e32 v3, 4, v2
	v_lshrrev_b32_e32 v1, 26, v1
	v_bitop3_b32 v2, v3, v2, 32 bitop3:0x6c
	v_add_u32_e32 v1, v8, v1
	v_ashrrev_i32_e32 v4, 31, v2
	v_ashrrev_i32_e32 v1, 6, v1
	v_lshrrev_b32_e32 v4, 26, v4
	v_lshlrev_b32_e32 v3, 3, v1
	v_add_u32_e32 v4, v2, v4
	v_and_b32_e32 v3, -16, v3
	v_ashrrev_i32_e32 v5, 6, v4
	v_and_b32_e32 v4, 0xc0, v4
	v_add_u32_e32 v3, v5, v3
	v_sub_u32_e32 v2, v2, v4
	v_mov_b32_e32 v7, 1
	v_lshlrev_b32_e32 v1, 5, v1
	v_ashrrev_i16_sdwa v2, v7, sext(v2) dst_sel:DWORD dst_unused:UNUSED_PAD src0_sel:DWORD src1_sel:BYTE_0
	v_lshlrev_b32_e32 v4, 1, v3
	v_lshrrev_b32_e32 v6, 2, v3
	v_and_b32_e32 v5, 3, v5
	s_mov_b32 s3, 0x7fffe0
	v_and_b32_e32 v1, 32, v1
	v_bfe_i32 v2, v2, 0, 16
	v_and_b32_e32 v4, 24, v4
	v_and_b32_e32 v6, 4, v6
	v_and_or_b32 v5, v3, s3, v5
	v_or3_b32 v4, v5, v6, v4
	v_add_lshl_u32 v1, v1, v2, 1
	v_add_u32_e32 v0, 0x2000, v0
	v_lshl_add_u32 v160, v3, 11, v1
	v_lshl_add_u32 v232, v4, 9, v1
	v_ashrrev_i32_e32 v1, 31, v0
	v_lshrrev_b32_e32 v1, 22, v1
	v_add_u32_e32 v1, v0, v1
	v_ashrrev_i32_e32 v1, 10, v1
	v_mul_i32_i24_e32 v2, 0x400, v1
	v_sub_u32_e32 v0, v0, v2
	v_lshrrev_b32_e32 v2, 4, v0
	v_bitop3_b32 v0, v2, v0, 32 bitop3:0x6c
	v_ashrrev_i32_e32 v3, 31, v0
	v_lshrrev_b32_e32 v3, 26, v3
	s_add_u32 s34, s12, 0x17a00000
	v_lshlrev_b32_e32 v2, 3, v1
	v_add_u32_e32 v3, v0, v3
	s_addc_u32 s35, s11, 0
	v_and_b32_e32 v2, -16, v2
	v_ashrrev_i32_e32 v4, 6, v3
	s_add_u32 s36, s12, 0x2200000
	v_add_u32_e32 v2, v4, v2
	v_and_b32_e32 v4, 3, v4
	s_addc_u32 s37, s11, 0
	v_and_or_b32 v4, v2, s3, v4
	s_ashr_i32 s3, s10, 6
	s_ashr_i32 s21, s20, 31
	s_ashr_i32 s5, s4, 31
	s_ashr_i32 s2, s10, 8
	v_and_b32_e32 v3, 0xc0, v3
	s_lshl_b32 s38, s3, 10
	s_lshl_b64 s[6:7], s[20:21], 19
	s_lshl_b64 s[8:9], s[4:5], 17
	v_sub_u32_e32 v0, v0, v3
	s_add_u32 s24, s36, s8
	v_lshlrev_b32_e32 v1, 5, v1
	v_ashrrev_i16_sdwa v0, v7, sext(v0) dst_sel:DWORD dst_unused:UNUSED_PAD src0_sel:DWORD src1_sel:BYTE_0
	v_lshlrev_b32_e32 v3, 1, v2
	v_lshrrev_b32_e32 v5, 2, v2
	s_addc_u32 s25, s37, s9
	s_add_i32 s39, s38, 0
	v_and_b32_e32 v1, 32, v1
	v_bfe_i32 v0, v0, 0, 16
	v_and_b32_e32 v3, 24, v3
	v_and_b32_e32 v5, 4, v5
	s_add_i32 m0, s39, 0x10000
	v_or3_b32 v3, v4, v5, v3
	v_add_lshl_u32 v0, v1, v0, 1
	global_load_lds_dwordx4 v232, s[24:25]
	s_add_i32 m0, s39, 0x12000
	v_lshl_add_u32 v164, v3, 9, v0
	s_add_u32 s8, s24, 0x10000
	global_load_lds_dwordx4 v164, s[24:25]
	s_addc_u32 s9, s25, 0
	s_add_i32 m0, s39, 0x14000
	v_lshl_add_u32 v162, v2, 11, v0
	global_load_lds_dwordx4 v232, s[8:9]
	s_add_i32 m0, s39, 0x16000
	s_add_u32 s22, s34, s6
	s_addc_u32 s23, s35, s7
	s_add_i32 s40, s39, 0x2000
	global_load_lds_dwordx4 v164, s[8:9]
	s_mov_b32 m0, s39
	s_add_u32 s6, s22, 0x40000
	global_load_lds_dwordx4 v160, s[22:23]
	s_mov_b32 m0, s40
	s_addc_u32 s7, s23, 0
	s_add_i32 s41, s39, 0x4000
	global_load_lds_dwordx4 v162, s[22:23]
	s_mov_b32 m0, s41
	s_add_i32 s42, s39, 0x6000
	global_load_lds_dwordx4 v160, s[6:7]
	s_mov_b32 m0, s42
	v_mov_b32_e32 v165, v233
	global_load_lds_dwordx4 v162, s[6:7]
	v_mov_b32_e32 v161, v233
	v_mov_b32_e32 v163, v233
	s_cmp_eq_u32 s2, 1
	v_lshl_add_u64 v[6:7], s[24:25], 0, v[232:233]
	v_lshl_add_u64 v[4:5], s[24:25], 0, v[164:165]
	v_lshl_add_u64 v[0:1], s[22:23], 0, v[160:161]
	s_cselect_b64 s[6:7], -1, 0
	s_cmp_lg_u32 s2, 1
	v_lshl_add_u64 v[2:3], s[22:23], 0, v[162:163]
	s_cbranch_scc1 .LBB0_1009
	s_setprio 1
	s_barrier

.LBB0_1152:
	v_ashrrev_i32_e32 v1, 31, v14
	v_lshrrev_b32_e32 v1, 26, v1
	v_add_u32_e32 v1, v14, v1
	v_ashrrev_i32_e32 v8, 6, v1
	v_bfe_i32 v1, v14, 27, 1
	v_lshlrev_b32_e32 v0, 4, v14
	v_lshrrev_b32_e32 v1, 22, v1
	v_add_u32_e32 v1, v0, v1
	v_and_b32_e32 v1, 0xfffffc00, v1
	v_sub_u32_e32 v1, v0, v1
	v_lshrrev_b32_e32 v2, 4, v1
	v_bitop3_b32 v1, v2, v1, 32 bitop3:0x6c
	v_ashrrev_i32_e32 v3, 31, v1
	v_lshrrev_b32_e32 v3, 26, v3
	v_add_u32_e32 v3, v1, v3
	v_lshlrev_b32_e32 v2, 3, v8
	v_ashrrev_i32_e32 v9, 6, v3
	v_and_b32_e32 v3, 0xc0, v3
	v_and_b32_e32 v2, -16, v2
	v_sub_u32_e32 v1, v1, v3
	v_mov_b32_e32 v6, 1
	v_add_u32_e32 v2, v9, v2
	v_ashrrev_i16_sdwa v1, v6, sext(v1) dst_sel:DWORD dst_unused:UNUSED_PAD src0_sel:DWORD src1_sel:BYTE_0
	v_lshlrev_b32_e32 v4, 5, v8
	v_bfe_i32 v10, v1, 0, 16
	v_lshlrev_b32_e32 v1, 1, v2
	v_lshrrev_b32_e32 v3, 2, v2
	v_and_b32_e32 v5, 3, v9
	s_mov_b32 s15, 0x1fffe0
	v_and_b32_e32 v4, 32, v4
	v_and_b32_e32 v1, 24, v1
	v_and_b32_e32 v3, 4, v3
	v_and_or_b32 v5, v2, s15, v5
	v_or3_b32 v1, v5, v3, v1
	v_add_lshl_u32 v3, v4, v10, 1
	v_add_u32_e32 v0, 0x2000, v0
	v_lshl_add_u32 v232, v1, 11, v3
	v_ashrrev_i32_e32 v1, 31, v0
	v_lshrrev_b32_e32 v1, 22, v1
	v_add_u32_e32 v1, v0, v1
	v_ashrrev_i32_e32 v11, 10, v1
	v_mul_i32_i24_e32 v1, 0x400, v11
	s_ashr_i32 s19, s18, 6
	s_ashr_i32 s5, s18, 8
	v_sub_u32_e32 v0, v0, v1
	s_lshl_b32 s41, s19, 10
	v_lshrrev_b32_e32 v1, 4, v0
	s_add_u32 s42, s16, 0x1ba00000
	v_bitop3_b32 v0, v1, v0, 32 bitop3:0x6c
	s_addc_u32 s43, s17, 0
	v_lshl_add_u32 v144, v2, 11, v3
	v_ashrrev_i32_e32 v2, 31, v0
	s_add_u32 s44, s16, 0x2400000
	v_lshrrev_b32_e32 v2, 26, v2
	s_addc_u32 s45, s17, 0
	s_add_i32 s4, s14, s4
	v_lshlrev_b32_e32 v1, 3, v11
	v_add_u32_e32 v2, v0, v2
	s_ashr_i32 s14, s4, 31
	v_and_b32_e32 v1, -16, v1
	v_ashrrev_i32_e32 v12, 6, v2
	s_lshr_b32 s14, s14, 27
	v_add_u32_e32 v1, v12, v1
	v_and_b32_e32 v4, 3, v12
	s_add_i32 s14, s4, s14
	v_and_or_b32 v4, v1, s15, v4
	s_ashr_i32 s15, s14, 5
	s_and_b32 s14, s14, 0xffe0
	s_sub_i32 s14, s4, s14
	s_bfe_i32 s4, s14, 0x80000
	s_bfe_u32 s4, s4, 0x3000c
	s_add_i32 s20, s14, s4
	s_bfe_i32 s4, s20, 0x80000
	s_and_b32 s20, s20, 0xf8
	s_sub_i32 s14, s14, s20
	s_lshl_b32 s15, s15, 3
	s_sext_i32_i16 s4, s4
	s_sext_i32_i8 s14, s14
	s_lshr_b32 s4, s4, 3
	s_add_i32 s28, s15, s14
	v_and_b32_e32 v2, 0xc0, v2
	s_ashr_i32 s29, s28, 31
	s_bfe_i64 s[20:21], s[4:5], 0x100000
	v_sub_u32_e32 v0, v0, v2
	s_lshl_b64 s[14:15], s[28:29], 19
	s_lshl_b64 s[20:21], s[20:21], 19
	v_ashrrev_i16_sdwa v0, v6, sext(v0) dst_sel:DWORD dst_unused:UNUSED_PAD src0_sel:DWORD src1_sel:BYTE_0
	s_add_u32 s30, s44, s20
	v_lshlrev_b32_e32 v3, 5, v11
	v_bfe_i32 v13, v0, 0, 16
	v_lshlrev_b32_e32 v0, 1, v1
	v_lshrrev_b32_e32 v2, 2, v1
	s_addc_u32 s31, s45, s21
	s_add_i32 s29, s41, 0
	v_and_b32_e32 v3, 32, v3
	v_and_b32_e32 v0, 24, v0
	v_and_b32_e32 v2, 4, v2
	s_add_i32 m0, s29, 0x10000
	v_or3_b32 v0, v4, v2, v0
	v_add_lshl_u32 v2, v3, v13, 1
	global_load_lds_dwordx4 v232, s[30:31]
	s_add_i32 m0, s29, 0x12000
	v_lshl_add_u32 v148, v0, 11, v2
	s_add_u32 s20, s30, 0x40000
	global_load_lds_dwordx4 v148, s[30:31]
	s_addc_u32 s21, s31, 0
	s_add_i32 m0, s29, 0x14000
	v_lshl_add_u32 v146, v1, 11, v2
	global_load_lds_dwordx4 v232, s[20:21]
	s_add_i32 m0, s29, 0x16000
	s_add_u32 s34, s42, s14
	s_addc_u32 s35, s43, s15
	s_add_i32 s46, s29, 0x2000
	global_load_lds_dwordx4 v148, s[20:21]
	s_mov_b32 m0, s29
	s_add_u32 s14, s34, 0x40000
	global_load_lds_dwordx4 v144, s[34:35]
	s_mov_b32 m0, s46
	s_addc_u32 s15, s35, 0
	s_add_i32 s47, s29, 0x4000
	global_load_lds_dwordx4 v146, s[34:35]
	s_mov_b32 m0, s47
	s_add_i32 s48, s29, 0x6000
	global_load_lds_dwordx4 v144, s[14:15]
	s_mov_b32 m0, s48
	v_mov_b32_e32 v149, v233
	global_load_lds_dwordx4 v146, s[14:15]
	v_mov_b32_e32 v145, v233
	v_mov_b32_e32 v147, v233
	s_cmp_eq_u32 s5, 1
	v_lshl_add_u64 v[6:7], s[30:31], 0, v[232:233]
	v_lshl_add_u64 v[4:5], s[30:31], 0, v[148:149]
	v_lshl_add_u64 v[0:1], s[34:35], 0, v[144:145]
	s_cselect_b64 s[14:15], -1, 0
	s_cmp_lg_u32 s5, 1
	v_lshl_add_u64 v[2:3], s[34:35], 0, v[146:147]
	s_cbranch_scc1 .LBB0_1154
	s_setprio 1
	s_barrier

.LBB0_1219:
	s_setprio 0
	s_cmp_le_i32 s86, s40
	s_cselect_b64 s[0:1], -1, 0
	s_and_b64 s[4:5], s[0:1], s[36:37]
	s_andn2_b64 vcc, exec, s[4:5]
	s_cbranch_vccnz .LBB0_1239
	v_mbcnt_lo_u32_b32 v0, -1, 0
	v_mbcnt_hi_u32_b32 v0, -1, v0
	s_mov_b32 s6, s74
	v_add_u32_e32 v0, s88, v0
	s_mov_b32 s10, s73
	v_mov_b32_e32 v1, s75
	ds_read_b64 v[2:3], v1
	v_readlane_b32 s4, v254, 12
	v_readfirstlane_b32 s12, v0
	s_ashr_i32 s12, s12, 3
	v_mov_b32_e32 v1, s4
	v_readlane_b32 s4, v254, 18
	s_waitcnt lgkmcnt(0)
	v_readfirstlane_b32 s9, v3
	v_readfirstlane_b32 s8, v2
	ds_read_b64 v[2:3], v1
	v_mov_b32_e32 v1, s4
	v_readlane_b32 s4, v254, 19
	ds_read_b64 v[4:5], v1
	s_lshl_b32 s10, s10, 6
	v_mov_b32_e32 v1, s4
	ds_read_b64 v[6:7], v1
	s_and_b32 s12, s12, -8
	s_add_i32 s10, s10, s12
	s_waitcnt lgkmcnt(0)
	v_readfirstlane_b32 s7, v3
	v_readfirstlane_b32 s20, v2
	v_readfirstlane_b32 s4, v5
	v_readfirstlane_b32 s5, v4
	v_readfirstlane_b32 s11, v7
	s_cmpk_gt_i32 s10, 0x7fff
	v_readfirstlane_b32 s12, v6
	s_cbranch_scc1 .LBB0_1239
	v_readlane_b32 s48, v254, 32
	v_readlane_b32 s49, v254, 33
	s_mov_b32 s17, s49
	s_lshl_b32 s16, s77, 10
	s_mov_b32 s13, s49
	v_readlane_b32 s50, v254, 34
	v_readlane_b32 s51, v254, 35
	v_readlane_b32 s52, v254, 36
	v_readlane_b32 s53, v254, 37
	v_readlane_b32 s54, v254, 38
	v_readlane_b32 s55, v254, 39
	v_readlane_b32 s56, v254, 40
	v_readlane_b32 s57, v254, 41
	v_readlane_b32 s58, v254, 42
	v_readlane_b32 s59, v254, 43
	v_readlane_b32 s60, v254, 44
	v_readlane_b32 s61, v254, 45
	v_readlane_b32 s62, v254, 46
	v_readlane_b32 s63, v254, 47
	v_writelane_b32 v254, s12, 32
	v_and_b32_e32 v0, 63, v0
	v_lshlrev_b32_e32 v232, 4, v0
	v_writelane_b32 v254, s13, 33
	v_writelane_b32 v254, s14, 34
	v_writelane_b32 v254, s15, 35
	v_writelane_b32 v254, s16, 36
	v_writelane_b32 v254, s17, 37
	v_writelane_b32 v254, s18, 38
	v_writelane_b32 v254, s19, 39
	v_writelane_b32 v254, s20, 40
	v_writelane_b32 v254, s21, 41
	v_writelane_b32 v254, s22, 42
	v_writelane_b32 v254, s23, 43
	v_writelane_b32 v254, s24, 44
	v_writelane_b32 v254, s25, 45
	v_writelane_b32 v254, s26, 46
	v_writelane_b32 v254, s27, 47
	s_lshl_b64 s[14:15], s[16:17], 2
	s_add_u32 s12, s12, s14
	s_addc_u32 s13, s11, s15
	s_add_u32 s14, s5, s14
	s_addc_u32 s15, s4, s15
	v_lshl_add_u64 v[136:137], s[12:13], 0, v[232:233]
	s_lshl_b32 s12, s6, 6
	s_ashr_i32 s11, s10, 31
	s_ashr_i32 s13, s12, 31
	s_lshl_b64 s[18:19], s[10:11], 11
	v_lshl_add_u64 v[134:135], s[14:15], 0, v[232:233]
	s_lshl_b64 s[14:15], s[10:11], 3
	s_lshl_b64 s[16:17], s[12:13], 3
	v_lshl_or_b32 v138, v0, 3, s18
	v_mov_b32_e32 v139, s19
	s_lshl_b64 s[18:19], s[12:13], 11
	s_lshl_b64 s[22:23], s[10:11], 12
	s_add_u32 s6, s20, s22
	s_addc_u32 s7, s7, s23
	v_cmp_eq_u32_e64 s[4:5], 0, v0
	v_lshl_add_u64 v[0:1], s[6:7], 0, v[232:233]
	s_mov_b64 s[6:7], 0x7c00
	v_lshl_add_u64 v[140:141], v[0:1], 0, s[6:7]
	s_lshl_b64 s[20:21], s[12:13], 12
	s_branch .LBB0_1223

.LBB0_1294:
	s_andn2_b64 vcc, exec, s[4:5]
	s_cbranch_vccnz .LBB0_1346
	v_ashrrev_i32_e32 v1, 31, v11
	v_lshrrev_b32_e32 v1, 26, v1
	v_add_u32_e32 v1, v11, v1
	v_ashrrev_i32_e32 v8, 6, v1
	v_bfe_i32 v1, v11, 27, 1
	v_lshlrev_b32_e32 v0, 4, v11
	v_lshrrev_b32_e32 v1, 22, v1
	v_add_u32_e32 v1, v0, v1
	v_and_b32_e32 v1, 0xfffffc00, v1
	v_sub_u32_e32 v1, v0, v1
	v_lshrrev_b32_e32 v2, 4, v1
	v_bitop3_b32 v1, v2, v1, 32 bitop3:0x6c
	v_ashrrev_i32_e32 v3, 31, v1
	v_lshrrev_b32_e32 v3, 26, v3
	v_add_u32_e32 v3, v1, v3
	v_lshlrev_b32_e32 v2, 3, v8
	v_ashrrev_i32_e32 v9, 6, v3
	v_and_b32_e32 v3, 0xc0, v3
	v_and_b32_e32 v2, -16, v2
	v_sub_u32_e32 v1, v1, v3
	v_mov_b32_e32 v6, 1
	v_add_u32_e32 v2, v9, v2
	v_ashrrev_i16_sdwa v1, v6, sext(v1) dst_sel:DWORD dst_unused:UNUSED_PAD src0_sel:DWORD src1_sel:BYTE_0
	v_lshlrev_b32_e32 v4, 5, v8
	v_bfe_i32 v10, v1, 0, 16
	v_lshlrev_b32_e32 v1, 1, v2
	v_lshrrev_b32_e32 v3, 2, v2
	v_and_b32_e32 v5, 3, v9
	s_mov_b32 s5, 0x1fffe0
	v_and_b32_e32 v4, 32, v4
	v_and_b32_e32 v1, 24, v1
	v_and_b32_e32 v3, 4, v3
	v_and_or_b32 v5, v2, s5, v5
	v_or3_b32 v1, v5, v3, v1
	v_add_lshl_u32 v3, v4, v10, 1
	v_add_u32_e32 v0, 0x2000, v0
	v_lshl_add_u32 v232, v1, 11, v3
	v_ashrrev_i32_e32 v1, 31, v0
	v_lshrrev_b32_e32 v1, 22, v1
	v_add_u32_e32 v1, v0, v1
	v_ashrrev_i32_e32 v12, 10, v1
	v_mul_i32_i24_e32 v1, 0x400, v12
	v_sub_u32_e32 v0, v0, v1
	v_lshrrev_b32_e32 v1, 4, v0
	v_bitop3_b32 v0, v1, v0, 32 bitop3:0x6c
	v_lshl_add_u32 v128, v2, 11, v3
	v_ashrrev_i32_e32 v2, 31, v0
	v_lshrrev_b32_e32 v2, 26, v2
	s_add_u32 s34, s10, 0x3a00000
	v_lshlrev_b32_e32 v1, 3, v12
	v_add_u32_e32 v2, v0, v2
	s_addc_u32 s35, s11, 0
	v_and_b32_e32 v1, -16, v1
	v_ashrrev_i32_e32 v13, 6, v2
	s_add_u32 s36, s10, 0x1200000
	v_add_u32_e32 v1, v13, v1
	v_and_b32_e32 v4, 3, v13
	s_addc_u32 s37, s11, 0
	v_and_b32_e32 v2, 0xc0, v2
	v_and_or_b32 v4, v1, s5, v4
	s_ashr_i32 s5, s12, 6
	s_ashr_i32 s23, s22, 31
	s_ashr_i32 s7, s6, 31
	s_ashr_i32 s4, s12, 8
	v_sub_u32_e32 v0, v0, v2
	s_lshl_b32 s38, s5, 10
	s_lshl_b64 s[8:9], s[22:23], 19
	s_lshl_b64 s[14:15], s[6:7], 19
	v_ashrrev_i16_sdwa v0, v6, sext(v0) dst_sel:DWORD dst_unused:UNUSED_PAD src0_sel:DWORD src1_sel:BYTE_0
	s_add_u32 s24, s36, s14
	v_lshlrev_b32_e32 v3, 5, v12
	v_bfe_i32 v14, v0, 0, 16
	v_lshlrev_b32_e32 v0, 1, v1
	v_lshrrev_b32_e32 v2, 2, v1
	s_addc_u32 s25, s37, s15
	s_add_i32 s39, s38, 0
	v_and_b32_e32 v3, 32, v3
	v_and_b32_e32 v0, 24, v0
	v_and_b32_e32 v2, 4, v2
	s_add_i32 m0, s39, 0x10000
	v_or3_b32 v0, v4, v2, v0
	v_add_lshl_u32 v2, v3, v14, 1
	global_load_lds_dwordx4 v232, s[24:25]
	s_add_i32 m0, s39, 0x12000
	v_lshl_add_u32 v132, v0, 11, v2
	s_add_u32 s14, s24, 0x40000
	global_load_lds_dwordx4 v132, s[24:25]
	s_addc_u32 s15, s25, 0
	s_add_i32 m0, s39, 0x14000
	v_lshl_add_u32 v130, v1, 11, v2
	global_load_lds_dwordx4 v232, s[14:15]
	s_add_i32 m0, s39, 0x16000
	s_add_u32 s26, s34, s8
	s_addc_u32 s27, s35, s9
	s_add_i32 s40, s39, 0x2000
	global_load_lds_dwordx4 v132, s[14:15]
	s_mov_b32 m0, s39
	s_add_u32 s8, s26, 0x40000
	global_load_lds_dwordx4 v128, s[26:27]
	s_mov_b32 m0, s40
	s_addc_u32 s9, s27, 0
	s_add_i32 s41, s39, 0x4000
	global_load_lds_dwordx4 v130, s[26:27]
	s_mov_b32 m0, s41
	s_add_i32 s42, s39, 0x6000
	global_load_lds_dwordx4 v128, s[8:9]
	s_mov_b32 m0, s42
	v_mov_b32_e32 v133, v233
	global_load_lds_dwordx4 v130, s[8:9]
	v_mov_b32_e32 v129, v233
	v_mov_b32_e32 v131, v233
	s_cmp_eq_u32 s4, 1
	v_lshl_add_u64 v[6:7], s[24:25], 0, v[232:233]
	v_lshl_add_u64 v[4:5], s[24:25], 0, v[132:133]
	v_lshl_add_u64 v[0:1], s[26:27], 0, v[128:129]
	s_cselect_b64 s[8:9], -1, 0
	s_cmp_lg_u32 s4, 1
	v_lshl_add_u64 v[2:3], s[26:27], 0, v[130:131]
	s_cbranch_scc1 .LBB0_1297
	s_setprio 1
	s_barrier

.LBB0_1352:
	s_andn2_b64 vcc, exec, s[4:5]
	s_cbranch_vccnz .LBB0_1404
	v_ashrrev_i32_e32 v1, 31, v11
	v_lshrrev_b32_e32 v1, 26, v1
	v_add_u32_e32 v1, v11, v1
	v_ashrrev_i32_e32 v8, 6, v1
	v_bfe_i32 v1, v11, 27, 1
	v_lshlrev_b32_e32 v0, 4, v11
	v_lshrrev_b32_e32 v1, 22, v1
	v_add_u32_e32 v1, v0, v1
	v_and_b32_e32 v1, 0xfffffc00, v1
	v_sub_u32_e32 v1, v0, v1
	v_lshrrev_b32_e32 v2, 4, v1
	v_bitop3_b32 v1, v2, v1, 32 bitop3:0x6c
	v_ashrrev_i32_e32 v3, 31, v1
	v_lshrrev_b32_e32 v3, 26, v3
	v_add_u32_e32 v3, v1, v3
	v_lshlrev_b32_e32 v2, 3, v8
	v_ashrrev_i32_e32 v9, 6, v3
	v_and_b32_e32 v3, 0xc0, v3
	v_and_b32_e32 v2, -16, v2
	v_sub_u32_e32 v1, v1, v3
	v_mov_b32_e32 v6, 1
	v_add_u32_e32 v2, v9, v2
	v_ashrrev_i16_sdwa v1, v6, sext(v1) dst_sel:DWORD dst_unused:UNUSED_PAD src0_sel:DWORD src1_sel:BYTE_0
	v_lshlrev_b32_e32 v4, 5, v8
	v_bfe_i32 v10, v1, 0, 16
	v_lshlrev_b32_e32 v1, 1, v2
	v_lshrrev_b32_e32 v3, 2, v2
	v_and_b32_e32 v5, 3, v9
	s_mov_b32 s5, 0x1fffe0
	v_and_b32_e32 v4, 32, v4
	v_and_b32_e32 v1, 24, v1
	v_and_b32_e32 v3, 4, v3
	v_and_or_b32 v5, v2, s5, v5
	v_or3_b32 v1, v5, v3, v1
	v_add_lshl_u32 v3, v4, v10, 1
	v_add_u32_e32 v0, 0x2000, v0
	v_lshl_add_u32 v232, v1, 11, v3
	v_ashrrev_i32_e32 v1, 31, v0
	v_lshrrev_b32_e32 v1, 22, v1
	v_add_u32_e32 v1, v0, v1
	v_ashrrev_i32_e32 v12, 10, v1
	v_mul_i32_i24_e32 v1, 0x400, v12
	v_sub_u32_e32 v0, v0, v1
	v_lshrrev_b32_e32 v1, 4, v0
	v_bitop3_b32 v0, v1, v0, 32 bitop3:0x6c
	v_lshl_add_u32 v128, v2, 11, v3
	v_ashrrev_i32_e32 v2, 31, v0
	v_lshrrev_b32_e32 v2, 26, v2
	s_add_u32 s34, s10, 0x3a00000
	v_lshlrev_b32_e32 v1, 3, v12
	v_add_u32_e32 v2, v0, v2
	s_addc_u32 s35, s11, 0
	v_and_b32_e32 v1, -16, v1
	v_ashrrev_i32_e32 v13, 6, v2
	s_add_u32 s36, s10, 0x2600000
	v_add_u32_e32 v1, v13, v1
	v_and_b32_e32 v4, 3, v13
	s_addc_u32 s37, s11, 0
	v_and_b32_e32 v2, 0xc0, v2
	v_and_or_b32 v4, v1, s5, v4
	s_ashr_i32 s5, s12, 6
	s_ashr_i32 s23, s22, 31
	s_ashr_i32 s7, s6, 31
	s_ashr_i32 s4, s12, 8
	v_sub_u32_e32 v0, v0, v2
	s_lshl_b32 s38, s5, 10
	s_lshl_b64 s[8:9], s[22:23], 19
	s_lshl_b64 s[14:15], s[6:7], 19
	v_ashrrev_i16_sdwa v0, v6, sext(v0) dst_sel:DWORD dst_unused:UNUSED_PAD src0_sel:DWORD src1_sel:BYTE_0
	s_add_u32 s24, s36, s14
	v_lshlrev_b32_e32 v3, 5, v12
	v_bfe_i32 v14, v0, 0, 16
	v_lshlrev_b32_e32 v0, 1, v1
	v_lshrrev_b32_e32 v2, 2, v1
	s_addc_u32 s25, s37, s15
	s_add_i32 s39, s38, 0
	v_and_b32_e32 v3, 32, v3
	v_and_b32_e32 v0, 24, v0
	v_and_b32_e32 v2, 4, v2
	s_add_i32 m0, s39, 0x10000
	v_or3_b32 v0, v4, v2, v0
	v_add_lshl_u32 v2, v3, v14, 1
	global_load_lds_dwordx4 v232, s[24:25]
	s_add_i32 m0, s39, 0x12000
	v_lshl_add_u32 v132, v0, 11, v2
	s_add_u32 s14, s24, 0x40000
	global_load_lds_dwordx4 v132, s[24:25]
	s_addc_u32 s15, s25, 0
	s_add_i32 m0, s39, 0x14000
	v_lshl_add_u32 v130, v1, 11, v2
	global_load_lds_dwordx4 v232, s[14:15]
	s_add_i32 m0, s39, 0x16000
	s_add_u32 s26, s34, s8
	s_addc_u32 s27, s35, s9
	s_add_i32 s40, s39, 0x2000
	global_load_lds_dwordx4 v132, s[14:15]
	s_mov_b32 m0, s39
	s_add_u32 s8, s26, 0x40000
	global_load_lds_dwordx4 v128, s[26:27]
	s_mov_b32 m0, s40
	s_addc_u32 s9, s27, 0
	s_add_i32 s41, s39, 0x4000
	global_load_lds_dwordx4 v130, s[26:27]
	s_mov_b32 m0, s41
	s_add_i32 s42, s39, 0x6000
	global_load_lds_dwordx4 v128, s[8:9]
	s_mov_b32 m0, s42
	v_mov_b32_e32 v133, v233
	global_load_lds_dwordx4 v130, s[8:9]
	v_mov_b32_e32 v129, v233
	v_mov_b32_e32 v131, v233
	s_cmp_eq_u32 s4, 1
	v_lshl_add_u64 v[6:7], s[24:25], 0, v[232:233]
	v_lshl_add_u64 v[4:5], s[24:25], 0, v[132:133]
	v_lshl_add_u64 v[0:1], s[26:27], 0, v[128:129]
	s_cselect_b64 s[8:9], -1, 0
	s_cmp_lg_u32 s4, 1
	v_lshl_add_u64 v[2:3], s[26:27], 0, v[130:131]
	s_cbranch_scc1 .LBB0_1355
	s_setprio 1
	s_barrier

.LBB0_1409:
	v_bfe_i32 v2, v8, 27, 1
	v_lshlrev_b32_e32 v0, 4, v8
	v_lshrrev_b32_e32 v2, 22, v2
	v_add_u32_e32 v2, v0, v2
	v_and_b32_e32 v2, 0xfffffc00, v2
	v_sub_u32_e32 v2, v0, v2
	v_ashrrev_i32_e32 v1, 31, v8
	v_lshrrev_b32_e32 v3, 4, v2
	v_lshrrev_b32_e32 v1, 26, v1
	v_bitop3_b32 v2, v3, v2, 32 bitop3:0x6c
	v_add_u32_e32 v1, v8, v1
	v_ashrrev_i32_e32 v4, 31, v2
	v_ashrrev_i32_e32 v1, 6, v1
	v_lshrrev_b32_e32 v4, 26, v4
	v_lshlrev_b32_e32 v3, 3, v1
	v_add_u32_e32 v4, v2, v4
	v_and_b32_e32 v3, -16, v3
	v_ashrrev_i32_e32 v5, 6, v4
	v_and_b32_e32 v4, 0xc0, v4
	v_add_u32_e32 v3, v5, v3
	v_sub_u32_e32 v2, v2, v4
	v_mov_b32_e32 v7, 1
	v_lshlrev_b32_e32 v1, 5, v1
	v_ashrrev_i16_sdwa v2, v7, sext(v2) dst_sel:DWORD dst_unused:UNUSED_PAD src0_sel:DWORD src1_sel:BYTE_0
	v_lshlrev_b32_e32 v4, 1, v3
	v_lshrrev_b32_e32 v6, 2, v3
	v_and_b32_e32 v5, 3, v5
	s_mov_b32 s7, 0x7fffe0
	v_and_b32_e32 v1, 32, v1
	v_bfe_i32 v2, v2, 0, 16
	v_and_b32_e32 v4, 24, v4
	v_and_b32_e32 v6, 4, v6
	v_and_or_b32 v5, v3, s7, v5
	v_or3_b32 v4, v5, v6, v4
	v_add_lshl_u32 v1, v1, v2, 1
	v_add_u32_e32 v0, 0x2000, v0
	v_lshl_add_u32 v148, v3, 9, v1
	v_lshl_add_u32 v232, v4, 9, v1
	v_ashrrev_i32_e32 v1, 31, v0
	v_lshrrev_b32_e32 v1, 22, v1
	v_add_u32_e32 v1, v0, v1
	v_ashrrev_i32_e32 v1, 10, v1
	v_mul_i32_i24_e32 v2, 0x400, v1
	v_sub_u32_e32 v0, v0, v2
	s_add_u32 s35, s8, 0x2a00000
	v_lshrrev_b32_e32 v2, 4, v0
	s_addc_u32 s36, s9, 0
	v_bitop3_b32 v0, v2, v0, 32 bitop3:0x6c
	s_add_u32 s37, s8, 0x2800000
	v_ashrrev_i32_e32 v3, 31, v0
	s_addc_u32 s38, s9, 0
	v_lshrrev_b32_e32 v3, 26, v3
	s_add_i32 s4, s6, s4
	v_lshlrev_b32_e32 v2, 3, v1
	v_add_u32_e32 v3, v0, v3
	s_ashr_i32 s6, s4, 31
	v_and_b32_e32 v2, -16, v2
	v_ashrrev_i32_e32 v4, 6, v3
	s_lshr_b32 s6, s6, 27
	v_add_u32_e32 v2, v4, v2
	v_and_b32_e32 v4, 3, v4
	s_add_i32 s6, s4, s6
	v_and_or_b32 v4, v2, s7, v4
	s_ashr_i32 s7, s6, 5
	s_and_b32 s6, s6, 0xffe0
	s_sub_i32 s6, s4, s6
	s_bfe_i32 s4, s6, 0x80000
	s_bfe_u32 s4, s4, 0x3000c
	s_add_i32 s14, s6, s4
	s_bfe_i32 s4, s14, 0x80000
	s_and_b32 s14, s14, 0xf8
	s_sub_i32 s6, s6, s14
	s_lshl_b32 s7, s7, 3
	s_sext_i32_i16 s4, s4
	s_sext_i32_i8 s6, s6
	s_ashr_i32 s5, s10, 8
	s_lshr_b32 s4, s4, 3
	s_add_i32 s22, s7, s6
	s_ashr_i32 s11, s10, 6
	s_ashr_i32 s23, s22, 31
	s_bfe_i64 s[14:15], s[4:5], 0x100000
	v_and_b32_e32 v3, 0xc0, v3
	s_lshl_b32 s39, s11, 10
	s_lshl_b64 s[6:7], s[22:23], 17
	s_lshl_b64 s[14:15], s[14:15], 17
	v_sub_u32_e32 v0, v0, v3
	s_add_u32 s26, s37, s14
	v_lshlrev_b32_e32 v1, 5, v1
	v_ashrrev_i16_sdwa v0, v7, sext(v0) dst_sel:DWORD dst_unused:UNUSED_PAD src0_sel:DWORD src1_sel:BYTE_0
	v_lshlrev_b32_e32 v3, 1, v2
	v_lshrrev_b32_e32 v5, 2, v2
	s_addc_u32 s27, s38, s15
	s_add_i32 s40, s39, 0
	v_and_b32_e32 v1, 32, v1
	v_bfe_i32 v0, v0, 0, 16
	v_and_b32_e32 v3, 24, v3
	v_and_b32_e32 v5, 4, v5
	s_add_i32 m0, s40, 0x10000
	v_or3_b32 v3, v4, v5, v3
	v_add_lshl_u32 v0, v1, v0, 1
	global_load_lds_dwordx4 v232, s[26:27]
	s_add_i32 m0, s40, 0x12000
	v_lshl_add_u32 v152, v3, 9, v0
	s_add_u32 s14, s26, 0x10000
	global_load_lds_dwordx4 v152, s[26:27]
	s_addc_u32 s15, s27, 0
	s_add_i32 m0, s40, 0x14000
	v_lshl_add_u32 v150, v2, 9, v0
	global_load_lds_dwordx4 v232, s[14:15]
	s_add_i32 m0, s40, 0x16000
	s_add_u32 s24, s35, s6
	s_addc_u32 s25, s36, s7
	s_add_i32 s41, s40, 0x2000
	global_load_lds_dwordx4 v152, s[14:15]
	s_mov_b32 m0, s40
	s_add_u32 s6, s24, 0x10000
	global_load_lds_dwordx4 v148, s[24:25]
	s_mov_b32 m0, s41
	s_addc_u32 s7, s25, 0
	s_add_i32 s42, s40, 0x4000
	global_load_lds_dwordx4 v150, s[24:25]
	s_mov_b32 m0, s42
	s_add_i32 s43, s40, 0x6000
	global_load_lds_dwordx4 v148, s[6:7]
	s_mov_b32 m0, s43
	v_mov_b32_e32 v153, v233
	global_load_lds_dwordx4 v150, s[6:7]
	v_mov_b32_e32 v149, v233
	v_mov_b32_e32 v151, v233
	s_cmp_eq_u32 s5, 1
	v_lshl_add_u64 v[6:7], s[26:27], 0, v[232:233]
	v_lshl_add_u64 v[4:5], s[26:27], 0, v[152:153]
	v_lshl_add_u64 v[0:1], s[24:25], 0, v[148:149]
	s_cselect_b64 s[6:7], -1, 0
	s_cmp_lg_u32 s5, 1
	v_lshl_add_u64 v[2:3], s[24:25], 0, v[150:151]
	s_cbranch_scc1 .LBB0_1411
	s_setprio 1
	s_barrier

.LBB0_1480:
	v_ashrrev_i32_e32 v1, 31, v12
	v_lshrrev_b32_e32 v1, 26, v1
	v_add_u32_e32 v1, v12, v1
	v_ashrrev_i32_e32 v8, 6, v1
	v_bfe_i32 v1, v12, 27, 1
	v_lshlrev_b32_e32 v0, 4, v12
	v_lshrrev_b32_e32 v1, 22, v1
	v_add_u32_e32 v1, v0, v1
	v_and_b32_e32 v1, 0xfffffc00, v1
	v_sub_u32_e32 v1, v0, v1
	v_lshrrev_b32_e32 v2, 4, v1
	v_bitop3_b32 v1, v2, v1, 32 bitop3:0x6c
	v_ashrrev_i32_e32 v3, 31, v1
	v_lshrrev_b32_e32 v3, 26, v3
	v_add_u32_e32 v3, v1, v3
	v_lshlrev_b32_e32 v2, 3, v8
	v_ashrrev_i32_e32 v9, 6, v3
	v_and_b32_e32 v3, 0xc0, v3
	v_and_b32_e32 v2, -16, v2
	v_sub_u32_e32 v1, v1, v3
	v_mov_b32_e32 v6, 1
	v_add_u32_e32 v2, v9, v2
	v_ashrrev_i16_sdwa v1, v6, sext(v1) dst_sel:DWORD dst_unused:UNUSED_PAD src0_sel:DWORD src1_sel:BYTE_0
	v_lshlrev_b32_e32 v4, 5, v8
	v_bfe_i32 v10, v1, 0, 16
	v_lshlrev_b32_e32 v1, 1, v2
	v_lshrrev_b32_e32 v3, 2, v2
	v_and_b32_e32 v5, 3, v9
	s_mov_b32 s9, 0x7ffe0
	v_and_b32_e32 v4, 32, v4
	v_and_b32_e32 v1, 24, v1
	v_and_b32_e32 v3, 4, v3
	v_and_or_b32 v5, v2, s9, v5
	v_or3_b32 v1, v5, v3, v1
	v_add_lshl_u32 v3, v4, v10, 1
	v_add_u32_e32 v0, 0x2000, v0
	v_lshl_add_u32 v232, v1, 13, v3
	v_ashrrev_i32_e32 v1, 31, v0
	v_lshrrev_b32_e32 v1, 22, v1
	v_add_u32_e32 v1, v0, v1
	v_ashrrev_i32_e32 v11, 10, v1
	v_mul_i32_i24_e32 v1, 0x400, v11
	v_sub_u32_e32 v0, v0, v1
	s_add_u32 s70, s12, 0x7a00000
	v_lshrrev_b32_e32 v1, 4, v0
	s_addc_u32 s71, s13, 0
	v_bitop3_b32 v0, v1, v0, 32 bitop3:0x6c
	s_add_u32 s72, s12, 0x1a00000
	v_lshl_add_u32 v180, v2, 13, v3
	v_ashrrev_i32_e32 v2, 31, v0
	s_addc_u32 s76, s13, 0
	v_lshrrev_b32_e32 v2, 26, v2
	s_add_i32 s4, s8, s4
	v_lshlrev_b32_e32 v1, 3, v11
	v_add_u32_e32 v2, v0, v2
	s_ashr_i32 s8, s4, 31
	v_and_b32_e32 v1, -16, v1
	v_ashrrev_i32_e32 v13, 6, v2
	s_lshr_b32 s8, s8, 27
	v_add_u32_e32 v1, v13, v1
	v_and_b32_e32 v4, 3, v13
	s_add_i32 s8, s4, s8
	v_and_or_b32 v4, v1, s9, v4
	s_ashr_i32 s9, s8, 5
	s_and_b32 s8, s8, 0xffe0
	s_sub_i32 s8, s4, s8
	s_bfe_i32 s4, s8, 0x80000
	s_bfe_u32 s4, s4, 0x3000c
	s_add_i32 s10, s8, s4
	s_bfe_i32 s4, s10, 0x80000
	s_and_b32 s10, s10, 0xf8
	s_sub_i32 s8, s8, s10
	s_lshl_b32 s9, s9, 3
	s_sext_i32_i16 s4, s4
	s_sext_i32_i8 s8, s8
	s_ashr_i32 s5, s18, 8
	s_lshr_b32 s4, s4, 3
	s_add_i32 s28, s9, s8
	v_and_b32_e32 v2, 0xc0, v2
	s_ashr_i32 s19, s18, 6
	s_ashr_i32 s29, s28, 31
	s_bfe_i64 s[10:11], s[4:5], 0x100000
	v_sub_u32_e32 v0, v0, v2
	s_lshl_b32 s77, s19, 10
	s_lshl_b64 s[8:9], s[28:29], 21
	s_lshl_b64 s[10:11], s[10:11], 21
	v_ashrrev_i16_sdwa v0, v6, sext(v0) dst_sel:DWORD dst_unused:UNUSED_PAD src0_sel:DWORD src1_sel:BYTE_0
	s_add_u32 s30, s72, s10
	v_lshlrev_b32_e32 v3, 5, v11
	v_bfe_i32 v14, v0, 0, 16
	v_lshlrev_b32_e32 v0, 1, v1
	v_lshrrev_b32_e32 v2, 2, v1
	s_addc_u32 s31, s76, s11
	s_add_i32 s78, s77, 0
	v_and_b32_e32 v3, 32, v3
	v_and_b32_e32 v0, 24, v0
	v_and_b32_e32 v2, 4, v2
	s_add_i32 m0, s78, 0x10000
	v_or3_b32 v0, v4, v2, v0
	v_add_lshl_u32 v2, v3, v14, 1
	global_load_lds_dwordx4 v232, s[30:31]
	s_add_i32 m0, s78, 0x12000
	v_lshl_add_u32 v184, v0, 13, v2
	s_add_u32 s10, s30, 0x100000
	global_load_lds_dwordx4 v184, s[30:31]
	s_addc_u32 s11, s31, 0
	s_add_i32 m0, s78, 0x14000
	v_lshl_add_u32 v182, v1, 13, v2
	global_load_lds_dwordx4 v232, s[10:11]
	s_add_i32 m0, s78, 0x16000
	s_add_u32 s34, s70, s8
	s_addc_u32 s35, s71, s9
	s_add_i32 s79, s78, 0x2000
	global_load_lds_dwordx4 v184, s[10:11]
	s_mov_b32 m0, s78
	s_add_u32 s8, s34, 0x100000
	global_load_lds_dwordx4 v180, s[34:35]
	s_mov_b32 m0, s79
	s_addc_u32 s9, s35, 0
	s_add_i32 s80, s78, 0x4000
	global_load_lds_dwordx4 v182, s[34:35]
	s_mov_b32 m0, s80
	s_add_i32 s81, s78, 0x6000
	global_load_lds_dwordx4 v180, s[8:9]
	s_mov_b32 m0, s81
	v_mov_b32_e32 v185, v233
	global_load_lds_dwordx4 v182, s[8:9]
	v_mov_b32_e32 v181, v233
	v_mov_b32_e32 v183, v233
	s_cmp_eq_u32 s5, 1
	v_lshl_add_u64 v[6:7], s[30:31], 0, v[232:233]
	v_lshl_add_u64 v[4:5], s[30:31], 0, v[184:185]
	v_lshl_add_u64 v[0:1], s[34:35], 0, v[180:181]
	s_cselect_b64 s[8:9], -1, 0
	s_cmp_lg_u32 s5, 1
	v_lshl_add_u64 v[2:3], s[34:35], 0, v[182:183]
	s_cbranch_scc1 .LBB0_1482
	s_setprio 1
	s_barrier

.LBB0_1547:
	s_setprio 0
	s_cmp_le_i32 s86, s40
	s_cselect_b64 s[8:9], -1, 0
	s_and_b64 s[0:1], s[8:9], s[36:37]
	s_andn2_b64 vcc, exec, s[0:1]
	s_mov_b32 s28, 0xfffff
	s_movk_i32 s29, 0x7e80
	v_readlane_b32 s30, v254, 23
	s_movk_i32 s31, 0x600
	s_mov_b64 s[34:35], 0x400000
	s_cbranch_vccnz .LBB0_1671
	v_mbcnt_lo_u32_b32 v0, -1, 0
	v_mbcnt_hi_u32_b32 v0, -1, v0
	s_mov_b32 s24, s74
	v_add_u32_e32 v189, s88, v0
	s_mov_b32 s25, s73
	v_mov_b32_e32 v0, s75
	ds_read_b64 v[0:1], v0
	v_readfirstlane_b32 s0, v189
	s_ashr_i32 s27, s0, 6
	s_lshl_b32 s0, s25, 3
	v_readlane_b32 s4, v254, 12
	s_add_i32 s26, s0, s27
	s_waitcnt lgkmcnt(0)
	v_readfirstlane_b32 s0, v0
	v_mov_b32_e32 v0, s4
	v_readfirstlane_b32 s1, v1
	ds_read_b64 v[0:1], v0
	v_readlane_b32 s48, v254, 32
	v_readlane_b32 s49, v254, 33
	s_mov_b32 s13, s49
	v_readlane_b32 s4, v254, 14
	s_waitcnt lgkmcnt(0)
	v_readfirstlane_b32 s21, v1
	v_readfirstlane_b32 s20, v0
	v_readlane_b32 s50, v254, 34
	v_readlane_b32 s51, v254, 35
	v_readlane_b32 s52, v254, 36
	v_readlane_b32 s53, v254, 37
	v_readlane_b32 s54, v254, 38
	v_readlane_b32 s55, v254, 39
	v_readlane_b32 s56, v254, 40
	v_readlane_b32 s57, v254, 41
	v_readlane_b32 s58, v254, 42
	v_readlane_b32 s59, v254, 43
	v_readlane_b32 s60, v254, 44
	v_readlane_b32 s61, v254, 45
	v_readlane_b32 s62, v254, 46
	v_readlane_b32 s63, v254, 47
	v_writelane_b32 v254, s12, 32
	v_mov_b32_e32 v0, s4
	ds_read_b64 v[0:1], v0
	v_writelane_b32 v254, s13, 33
	v_writelane_b32 v254, s14, 34
	v_writelane_b32 v254, s15, 35
	v_writelane_b32 v254, s16, 36
	v_writelane_b32 v254, s17, 37
	v_writelane_b32 v254, s18, 38
	v_writelane_b32 v254, s19, 39
	v_writelane_b32 v254, s20, 40
	v_writelane_b32 v254, s21, 41
	v_writelane_b32 v254, s22, 42
	v_writelane_b32 v254, s23, 43
	v_writelane_b32 v254, s24, 44
	s_mov_b32 s5, s49
	s_lshl_b32 s4, s77, 10
	v_writelane_b32 v254, s25, 45
	s_waitcnt lgkmcnt(0)
	v_readfirstlane_b32 s7, v0
	v_writelane_b32 v254, s26, 46
	s_lshl_b64 s[4:5], s[4:5], 2
	v_readfirstlane_b32 s6, v1
	v_writelane_b32 v254, s27, 47
	s_add_u32 s12, s7, s4
	s_addc_u32 s13, s6, s5
	v_readlane_b32 s6, v254, 16
	v_readlane_b32 s10, v254, 58
	v_readlane_b32 s11, v254, 59
	v_mov_b32_e32 v0, s6
	ds_read_b64 v[0:1], v0
	v_and_b32_e32 v191, 63, v189
	s_waitcnt lgkmcnt(0)
	v_readfirstlane_b32 s7, v0
	v_readfirstlane_b32 s6, v1
	s_add_u32 s14, s7, s4
	s_addc_u32 s15, s6, s5
	s_cmpk_lt_i32 s26, 0x1000
	s_cselect_b64 s[4:5], -1, 0
	v_cndmask_b32_e64 v0, 0, 1, s[4:5]
	s_mov_b64 s[6:7], -1
	s_and_b64 vcc, exec, s[10:11]
	v_cmp_ne_u32_e64 s[4:5], 1, v0
	s_cbranch_vccz .LBB0_1555
	s_and_b64 vcc, exec, s[4:5]
	s_cbranch_vccnz .LBB0_1554
	s_lshl_b32 s10, s26, 3
	s_cmp_lg_u64 s[20:21], 0
	s_cselect_b64 s[16:17], -1, 0
	s_ashr_i32 s11, s10, 31
	s_lshl_b32 s18, s24, 6
	s_lshl_b64 s[6:7], s[10:11], 12
	s_add_u32 s6, s20, s6
	v_lshlrev_b32_e32 v232, 4, v191
	s_addc_u32 s7, s21, s7
	v_lshl_add_u64 v[0:1], s[6:7], 0, v[232:233]
	s_mov_b64 s[6:7], 0x7c00
	s_ashr_i32 s19, s18, 31
	v_lshl_add_u64 v[134:135], s[12:13], 0, v[232:233]
	v_lshl_add_u64 v[136:137], s[14:15], 0, v[232:233]
	v_lshl_add_u64 v[138:139], v[0:1], 0, s[6:7]
	s_lshl_b64 s[22:23], s[18:19], 12
	s_branch .LBB0_1552
